# K ring 3-deep in 16 KiB static LDS: next tile's first 8 K fragment reads issued in the PV tail (single barrier per tile kept)
# baseline (speedup 1.0000x reference)
.Lfast_entry:
	s_waitcnt vmcnt(0)
	s_barrier
	s_mov_b32 s87, 0
	s_mov_b32 s88, 0x8000
	s_mov_b32 s89, 0x22000
	s_add_i32 s90, s55, 0x8000
	s_mov_b32 m0, s90
	s_nop 0
	global_load_lds_dwordx4 v254, s[74:75]
	s_add_i32 m0, s90, 0x1f80
	s_nop 0
	global_load_lds_dwordx4 v254, s[74:75] offset:128
	ds_read_b128 v[178:181], v226
	ds_read_b128 v[182:185], v226 offset:4096
	ds_read_b128 v[186:189], v227
	ds_read_b128 v[190:193], v227 offset:4096
	ds_read_b128 v[194:197], v228
	ds_read_b128 v[198:201], v228 offset:4096
	ds_read_b128 v[202:205], v230
	ds_read_b128 v[206:209], v230 offset:4096
	s_waitcnt lgkmcnt(0)
.Lfast_loop:
	s_waitcnt vmcnt(0)
	s_barrier
	s_add_u32 s80, s74, s42
	s_addc_u32 s81, s75, s43
	s_add_i32 s4, s55, 0x8000
	s_add_u32 s82, s76, s42
	s_addc_u32 s83, s77, s43
	s_add_u32 s84, s82, 0x54000
	s_addc_u32 s85, s83, 0
	s_add_i32 m0, s4, 0x4000
	s_nop 0
	global_load_lds_dwordx4 v255, s[82:83]
	s_add_i32 m0, s4, 0x6000
	s_nop 0
	global_load_lds_dwordx4 v255, s[84:85]
	s_cmp_eq_u32 s42, 0x52b0000
	s_cbranch_scc1 .Lfast_skipk0
	s_add_u32 s80, s80, 0xa8000
	s_addc_u32 s81, s81, 0
	s_add_i32 s90, s55, s89
	s_mov_b32 m0, s90
	s_nop 0
	global_load_lds_dwordx4 v254, s[80:81]
	s_add_i32 m0, s90, 0x1f80
	s_nop 0
	global_load_lds_dwordx4 v254, s[80:81] offset:128
.Lfast_skipk0:
	ds_read_b128 v[6:9], v236
	ds_read_b128 v[10:13], v236 offset:32
	ds_read_b128 v[14:17], v236 offset:64
	ds_read_b128 v[238:241], v236 offset:96
	s_waitcnt lgkmcnt(3)
	v_mfma_f32_32x32x16_bf16 v[162:177], v[178:181], v[6:9], 0
	v_mfma_f32_32x32x16_bf16 v[146:161], v[182:185], v[6:9], 0
	ds_read_b128 v[246:249], v236 offset:128
	ds_read_b128 v[250:253], v226 offset:8192
	ds_read_b128 v[6:9], v226 offset:12288
	s_waitcnt lgkmcnt(5)
	v_mfma_f32_32x32x16_bf16 v[162:177], v[186:189], v[10:13], v[162:177]
	v_mfma_f32_32x32x16_bf16 v[146:161], v[190:193], v[10:13], v[146:161]
	ds_read_b128 v[10:13], v236 offset:160
	s_waitcnt lgkmcnt(5)
	v_mfma_f32_32x32x16_bf16 v[162:177], v[194:197], v[14:17], v[162:177]
	v_mfma_f32_32x32x16_bf16 v[146:161], v[198:201], v[14:17], v[146:161]
	ds_read_b128 v[14:17], v227 offset:8192
	s_waitcnt lgkmcnt(5)
	v_mfma_f32_32x32x16_bf16 v[162:177], v[202:205], v[238:241], v[162:177]
	v_mfma_f32_32x32x16_bf16 v[146:161], v[206:209], v[238:241], v[146:161]
	ds_read_b128 v[238:241], v227 offset:12288
	s_waitcnt lgkmcnt(4)
	v_mfma_f32_32x32x16_bf16 v[194:209], v[250:253], v[246:249], 0
	s_waitcnt lgkmcnt(3)
	v_mfma_f32_32x32x16_bf16 v[178:193], v[6:9], v[246:249], 0
	ds_read_b128 v[246:249], v236 offset:192
	ds_read_b128 v[250:253], v228 offset:8192
	ds_read_b128 v[6:9], v228 offset:12288
	s_waitcnt lgkmcnt(4)
	v_mfma_f32_32x32x16_bf16 v[194:209], v[14:17], v[10:13], v[194:209]
	s_waitcnt lgkmcnt(3)
	v_mfma_f32_32x32x16_bf16 v[178:193], v[238:241], v[10:13], v[178:193]
	ds_read_b128 v[10:13], v236 offset:224
	ds_read_b128 v[14:17], v230 offset:8192
	ds_read_b128 v[238:241], v230 offset:12288
	s_waitcnt lgkmcnt(4)
	v_mfma_f32_32x32x16_bf16 v[194:209], v[250:253], v[246:249], v[194:209]
	s_waitcnt lgkmcnt(3)
	v_mfma_f32_32x32x16_bf16 v[178:193], v[6:9], v[246:249], v[178:193]
	s_waitcnt lgkmcnt(1)
	v_mfma_f32_32x32x16_bf16 v[194:209], v[14:17], v[10:13], v[194:209]
	s_waitcnt lgkmcnt(0)
	v_mfma_f32_32x32x16_bf16 v[178:193], v[238:241], v[10:13], v[178:193]
	v_exp_f32_e32 v166, v166
	v_exp_f32_e32 v167, v167
	v_exp_f32_e32 v168, v168
	v_exp_f32_e32 v169, v169
	s_nop 6
	v_exp_f32_e32 v2, v194
	v_exp_f32_e32 v194, v195
	v_exp_f32_e32 v195, v196
	v_exp_f32_e32 v196, v197
	v_exp_f32_e32 v197, v198
	v_exp_f32_e32 v198, v199
	v_exp_f32_e32 v199, v200
	v_exp_f32_e32 v200, v201
	v_exp_f32_e32 v201, v162
	v_exp_f32_e32 v237, v163
	v_exp_f32_e32 v238, v164
	v_exp_f32_e32 v239, v165
	v_cvt_pk_bf16_f32 v6, v201, v237
	v_cvt_pk_bf16_f32 v7, v238, v239
	v_cvt_pk_bf16_f32 v8, v166, v167
	v_cvt_pk_bf16_f32 v9, v168, v169
	ds_read_b64_tr_b16 v[10:11], v231 offset:16384
	ds_read_b64_tr_b16 v[12:13], v231 offset:18432
	v_cvt_pk_bf16_f32 v14, v2, v194
	ds_read_b64_tr_b16 v[162:163], v232 offset:16384
	ds_read_b64_tr_b16 v[164:165], v232 offset:18432
	v_cvt_pk_bf16_f32 v15, v195, v196
	v_cvt_pk_bf16_f32 v16, v197, v198
	v_cvt_pk_bf16_f32 v17, v199, v200
	s_waitcnt lgkmcnt(2)
	v_mfma_f32_32x32x16_bf16 v[82:97], v[6:9], v[10:13], v[82:97]
	v_exp_f32_e32 v202, v202
	v_exp_f32_e32 v203, v203
	v_exp_f32_e32 v204, v204
	v_exp_f32_e32 v205, v205
	v_exp_f32_e32 v206, v206
	v_exp_f32_e32 v207, v207
	v_exp_f32_e32 v208, v208
	v_mfma_f32_32x32x16_bf16 v[130:145], v[14:17], v[10:13], v[130:145]
	ds_read_b64_tr_b16 v[10:11], v233 offset:16384
	ds_read_b64_tr_b16 v[12:13], v233 offset:18432
	v_exp_f32_e32 v170, v170
	v_exp_f32_e32 v171, v171
	v_exp_f32_e32 v172, v172
	v_exp_f32_e32 v173, v173
	v_exp_f32_e32 v174, v174
	v_exp_f32_e32 v175, v175
	s_waitcnt lgkmcnt(2)
	v_mfma_f32_32x32x16_bf16 v[66:81], v[6:9], v[162:165], v[66:81]
	v_exp_f32_e32 v176, v176
	v_exp_f32_e32 v177, v177
	v_exp_f32_e32 v209, v209
	v_exp_f32_e32 v178, v178
	v_exp_f32_e32 v179, v179
	v_exp_f32_e32 v180, v180
	v_exp_f32_e32 v181, v181
	v_mfma_f32_32x32x16_bf16 v[114:129], v[14:17], v[162:165], v[114:129]
	ds_read_b64_tr_b16 v[162:163], v234 offset:16384
	ds_read_b64_tr_b16 v[164:165], v234 offset:18432
	v_add_f32_e32 v2, v178, v2
	v_add_f32_e32 v2, 0, v2
	v_add_f32_e32 v194, v179, v194
	v_add_f32_e32 v2, v194, v2
	v_add_f32_e32 v194, v180, v195
	s_waitcnt lgkmcnt(2)
	v_mfma_f32_32x32x16_bf16 v[34:49], v[6:9], v[10:13], v[34:49]
	v_add_f32_e32 v2, v194, v2
	v_add_f32_e32 v194, v181, v196
	v_add_f32_e32 v2, v194, v2
	v_exp_f32_e32 v182, v182
	v_exp_f32_e32 v183, v183
	v_exp_f32_e32 v184, v184
	v_exp_f32_e32 v194, v146
	v_mfma_f32_32x32x16_bf16 v[98:113], v[14:17], v[10:13], v[98:113]
	ds_read_b64_tr_b16 v[10:11], v231 offset:20480
	ds_read_b64_tr_b16 v[12:13], v231 offset:22528
	v_exp_f32_e32 v195, v147
	v_exp_f32_e32 v196, v148
	v_exp_f32_e32 v244, v149
	v_exp_f32_e32 v150, v150
	v_exp_f32_e32 v151, v151
	v_exp_f32_e32 v152, v152
	s_waitcnt lgkmcnt(2)
	v_mfma_f32_32x32x16_bf16 v[18:33], v[6:9], v[162:165], v[18:33]
	v_cvt_pk_bf16_f32 v6, v170, v171
	v_cvt_pk_bf16_f32 v7, v172, v173
	v_cvt_pk_bf16_f32 v8, v174, v175
	v_cvt_pk_bf16_f32 v9, v176, v177
	v_exp_f32_e32 v153, v153
	v_exp_f32_e32 v154, v154
	v_exp_f32_e32 v155, v155
	v_mfma_f32_32x32x16_bf16 v[50:65], v[14:17], v[162:165], v[50:65]
	v_cvt_pk_bf16_f32 v14, v202, v203
	ds_read_b64_tr_b16 v[162:163], v232 offset:20480
	ds_read_b64_tr_b16 v[164:165], v232 offset:22528
	v_cvt_pk_bf16_f32 v15, v204, v205
	v_cvt_pk_bf16_f32 v16, v206, v207
	v_cvt_pk_bf16_f32 v17, v208, v209
	v_exp_f32_e32 v156, v156
	s_waitcnt lgkmcnt(2)
	v_mfma_f32_32x32x16_bf16 v[82:97], v[6:9], v[10:13], v[82:97]
	v_exp_f32_e32 v157, v157
	v_exp_f32_e32 v158, v158
	v_exp_f32_e32 v159, v159
	v_exp_f32_e32 v160, v160
	v_exp_f32_e32 v161, v161
	s_sub_i32 s90, s88, s87
	v_add_u32_e32 v226, s90, v226
	v_add_u32_e32 v227, s90, v227
	v_add_u32_e32 v228, s90, v228
	v_add_u32_e32 v230, s90, v230
	s_mov_b32 s90, s87
	s_mov_b32 s87, s88
	s_mov_b32 s88, s89
	s_mov_b32 s89, s90
	s_add_u32 s42, s42, 0xa8000
	s_addc_u32 s43, s43, 0
	v_mfma_f32_32x32x16_bf16 v[130:145], v[14:17], v[10:13], v[130:145]
	ds_read_b64_tr_b16 v[10:11], v233 offset:20480
	ds_read_b64_tr_b16 v[12:13], v233 offset:22528
	s_waitcnt lgkmcnt(2)
	v_mfma_f32_32x32x16_bf16 v[66:81], v[6:9], v[162:165], v[66:81]
	v_mfma_f32_32x32x16_bf16 v[114:129], v[14:17], v[162:165], v[114:129]
	ds_read_b64_tr_b16 v[162:163], v234 offset:20480
	ds_read_b64_tr_b16 v[164:165], v234 offset:22528
	s_waitcnt lgkmcnt(0)
	v_mfma_f32_32x32x16_bf16 v[18:33], v[6:9], v[162:165], v[18:33]
	v_mfma_f32_32x32x16_bf16 v[50:65], v[14:17], v[162:165], v[50:65]
	v_exp_f32_e32 v162, v185
	v_add_f32_e32 v163, v182, v197
	v_add_f32_e32 v2, v163, v2
	v_add_f32_e32 v163, v183, v198
	v_add_f32_e32 v2, v163, v2
	v_exp_f32_e32 v163, v186
	v_exp_f32_e32 v164, v188
	v_mfma_f32_32x32x16_bf16 v[34:49], v[6:9], v[10:13], v[34:49]
	v_cvt_pk_bf16_f32 v6, v194, v195
	v_cvt_pk_bf16_f32 v7, v196, v244
	v_cvt_pk_bf16_f32 v8, v150, v151
	v_cvt_pk_bf16_f32 v9, v152, v153
	v_exp_f32_e32 v165, v189
	v_mfma_f32_32x32x16_bf16 v[98:113], v[14:17], v[10:13], v[98:113]
	ds_read_b64_tr_b16 v[10:11], v231 offset:24576
	ds_read_b64_tr_b16 v[12:13], v231 offset:26624
	v_cvt_pk_bf16_f32 v14, v178, v179
	v_cvt_pk_bf16_f32 v15, v180, v181
	v_cvt_pk_bf16_f32 v16, v182, v183
	v_cvt_pk_bf16_f32 v17, v184, v162
	ds_read_b64_tr_b16 v[146:147], v232 offset:24576
	ds_read_b64_tr_b16 v[148:149], v232 offset:26624
	v_add_f32_e32 v178, v165, v205
	s_waitcnt lgkmcnt(2)
	v_mfma_f32_32x32x16_bf16 v[82:97], v[6:9], v[10:13], v[82:97]
	v_exp_f32_e32 v179, v190
	s_nop 0
	v_add_f32_e32 v180, v179, v206
	v_mfma_f32_32x32x16_bf16 v[130:145], v[14:17], v[10:13], v[130:145]
	v_add_f32_e32 v10, v184, v199
	ds_read_b128 v[182:185], v226 offset:4096
	v_add_f32_e32 v2, v10, v2
	v_add_f32_e32 v10, v162, v200
	v_exp_f32_e32 v162, v187
	ds_read_b128 v[186:189], v227
	v_add_f32_e32 v2, v10, v2
	v_add_f32_e32 v10, v163, v202
	v_add_f32_e32 v2, v10, v2
	v_add_f32_e32 v10, v162, v203
	v_add_f32_e32 v2, v10, v2
	v_add_f32_e32 v10, v164, v204
	ds_read_b128 v[202:205], v230
	v_add_f32_e32 v2, v10, v2
	v_add_f32_e32 v2, v178, v2
	v_exp_f32_e32 v178, v191
	ds_read_b64_tr_b16 v[10:11], v233 offset:24576
	ds_read_b64_tr_b16 v[12:13], v233 offset:26624
	s_waitcnt lgkmcnt(5)
	v_mfma_f32_32x32x16_bf16 v[66:81], v[6:9], v[146:149], v[66:81]
	v_add_f32_e32 v2, v180, v2
	v_exp_f32_e32 v180, v192
	v_add_f32_e32 v181, v178, v207
	v_add_f32_e32 v2, v181, v2
	v_exp_f32_e32 v181, v193
	ds_read_b128 v[190:193], v227 offset:4096
	v_mfma_f32_32x32x16_bf16 v[114:129], v[14:17], v[146:149], v[114:129]
	ds_read_b64_tr_b16 v[146:147], v234 offset:24576
	ds_read_b64_tr_b16 v[148:149], v234 offset:26624
	s_waitcnt lgkmcnt(3)
	v_mfma_f32_32x32x16_bf16 v[34:49], v[6:9], v[10:13], v[34:49]
	v_mfma_f32_32x32x16_bf16 v[98:113], v[14:17], v[10:13], v[98:113]
	v_add_f32_e32 v10, v180, v208
	v_add_f32_e32 v2, v10, v2
	ds_read_b64_tr_b16 v[10:11], v231 offset:28672
	ds_read_b64_tr_b16 v[12:13], v231 offset:30720
	s_waitcnt lgkmcnt(2)
	v_mfma_f32_32x32x16_bf16 v[18:33], v[6:9], v[146:149], v[18:33]
	v_cvt_pk_bf16_f32 v6, v154, v155
	v_cvt_pk_bf16_f32 v7, v156, v157
	v_cvt_pk_bf16_f32 v8, v158, v159
	v_cvt_pk_bf16_f32 v9, v160, v161
	v_mfma_f32_32x32x16_bf16 v[50:65], v[14:17], v[146:149], v[50:65]
	v_cvt_pk_bf16_f32 v14, v163, v162
	v_cvt_pk_bf16_f32 v15, v164, v165
	v_cvt_pk_bf16_f32 v16, v179, v178
	v_cvt_pk_bf16_f32 v17, v180, v181
	v_add_f32_e32 v162, v181, v209
	ds_read_b128 v[178:181], v226
	ds_read_b128 v[206:209], v230 offset:4096
	v_add_f32_e32 v2, v162, v2
	v_add_f32_e32 v4, v4, v2
	v_add_f32_e32 v2, v194, v201
	ds_read_b128 v[198:201], v228 offset:4096
	s_waitcnt lgkmcnt(3)
	v_mfma_f32_32x32x16_bf16 v[82:97], v[6:9], v[10:13], v[82:97]
	v_add_f32_e32 v2, 0, v2
	ds_read_b64_tr_b16 v[146:147], v232 offset:28672
	ds_read_b64_tr_b16 v[148:149], v232 offset:30720
	v_mfma_f32_32x32x16_bf16 v[130:145], v[14:17], v[10:13], v[130:145]
	v_add_f32_e32 v10, v195, v237
	v_add_f32_e32 v2, v10, v2
	v_add_f32_e32 v10, v196, v238
	ds_read_b128 v[194:197], v228
	v_add_f32_e32 v2, v10, v2
	v_add_f32_e32 v10, v244, v239
	v_add_f32_e32 v2, v10, v2
	v_add_f32_e32 v10, v150, v166
	v_add_f32_e32 v2, v10, v2
	v_add_f32_e32 v10, v151, v167
	v_add_f32_e32 v2, v10, v2
	v_add_f32_e32 v10, v152, v168
	s_waitcnt lgkmcnt(1)
	v_mfma_f32_32x32x16_bf16 v[66:81], v[6:9], v[146:149], v[66:81]
	v_add_f32_e32 v2, v10, v2
	ds_read_b64_tr_b16 v[10:11], v233 offset:28672
	ds_read_b64_tr_b16 v[12:13], v233 offset:30720
	v_add_f32_e32 v150, v153, v169
	v_add_f32_e32 v2, v150, v2
	v_add_f32_e32 v150, v154, v170
	v_add_f32_e32 v2, v150, v2
	v_add_f32_e32 v150, v155, v171
	v_mfma_f32_32x32x16_bf16 v[114:129], v[14:17], v[146:149], v[114:129]
	ds_read_b64_tr_b16 v[146:147], v234 offset:28672
	ds_read_b64_tr_b16 v[148:149], v234 offset:30720
	v_add_f32_e32 v2, v150, v2
	v_add_f32_e32 v150, v156, v172
	v_add_f32_e32 v2, v150, v2
	v_add_f32_e32 v150, v157, v173
	v_add_f32_e32 v2, v150, v2
	s_waitcnt lgkmcnt(2)
	v_mfma_f32_32x32x16_bf16 v[34:49], v[6:9], v[10:13], v[34:49]
	v_mfma_f32_32x32x16_bf16 v[98:113], v[14:17], v[10:13], v[98:113]
	v_add_f32_e32 v10, v158, v174
	v_add_f32_e32 v2, v10, v2
	v_add_f32_e32 v10, v159, v175
	v_add_f32_e32 v2, v10, v2
	v_add_f32_e32 v10, v160, v176
	v_add_f32_e32 v2, v10, v2
	v_add_f32_e32 v10, v161, v177
	s_waitcnt lgkmcnt(0)
	v_mfma_f32_32x32x16_bf16 v[18:33], v[6:9], v[146:149], v[18:33]
	v_add_f32_e32 v2, v10, v2
	v_add_f32_e32 v235, v235, v2
	v_mfma_f32_32x32x16_bf16 v[50:65], v[14:17], v[146:149], v[50:65]
	s_waitcnt vmcnt(0)
	s_barrier
	s_cmp_eq_u32 s42, 0x5358000
	s_cbranch_scc1 .Lfast_skip_dma
	s_add_u32 s80, s74, s42
	s_addc_u32 s81, s75, s43
	s_add_i32 s4, s55, 0
	s_add_u32 s82, s76, s42
	s_addc_u32 s83, s77, s43
	s_add_u32 s84, s82, 0x54000
	s_addc_u32 s85, s83, 0
	s_add_i32 m0, s4, 0x4000
	s_nop 0
	global_load_lds_dwordx4 v255, s[82:83]
	s_add_i32 m0, s4, 0x6000
	s_nop 0
	global_load_lds_dwordx4 v255, s[84:85]
	s_add_u32 s80, s80, 0xa8000
	s_addc_u32 s81, s81, 0
	s_add_i32 s90, s55, s89
	s_mov_b32 m0, s90
	s_nop 0
	global_load_lds_dwordx4 v254, s[80:81]
	s_add_i32 m0, s90, 0x1f80
	s_nop 0
	global_load_lds_dwordx4 v254, s[80:81] offset:128
.Lfast_skip_dma:
	ds_read_b128 v[6:9], v236
	ds_read_b128 v[10:13], v236 offset:32
	ds_read_b128 v[14:17], v236 offset:64
	ds_read_b128 v[238:241], v236 offset:96
	s_waitcnt lgkmcnt(3)
	v_mfma_f32_32x32x16_bf16 v[162:177], v[178:181], v[6:9], 0
	v_mfma_f32_32x32x16_bf16 v[146:161], v[182:185], v[6:9], 0
	ds_read_b128 v[246:249], v236 offset:128
	ds_read_b128 v[250:253], v226 offset:8192
	ds_read_b128 v[6:9], v226 offset:12288
	s_waitcnt lgkmcnt(5)
	v_mfma_f32_32x32x16_bf16 v[162:177], v[186:189], v[10:13], v[162:177]
	v_mfma_f32_32x32x16_bf16 v[146:161], v[190:193], v[10:13], v[146:161]
	ds_read_b128 v[10:13], v236 offset:160
	s_waitcnt lgkmcnt(5)
	v_mfma_f32_32x32x16_bf16 v[162:177], v[194:197], v[14:17], v[162:177]
	v_mfma_f32_32x32x16_bf16 v[146:161], v[198:201], v[14:17], v[146:161]
	ds_read_b128 v[14:17], v227 offset:8192
	s_waitcnt lgkmcnt(5)
	v_mfma_f32_32x32x16_bf16 v[162:177], v[202:205], v[238:241], v[162:177]
	v_mfma_f32_32x32x16_bf16 v[146:161], v[206:209], v[238:241], v[146:161]
	ds_read_b128 v[238:241], v227 offset:12288
	s_waitcnt lgkmcnt(4)
	v_mfma_f32_32x32x16_bf16 v[194:209], v[250:253], v[246:249], 0
	s_waitcnt lgkmcnt(3)
	v_mfma_f32_32x32x16_bf16 v[178:193], v[6:9], v[246:249], 0
	ds_read_b128 v[246:249], v236 offset:192
	ds_read_b128 v[250:253], v228 offset:8192
	ds_read_b128 v[6:9], v228 offset:12288
	s_waitcnt lgkmcnt(4)
	v_mfma_f32_32x32x16_bf16 v[194:209], v[14:17], v[10:13], v[194:209]
	s_waitcnt lgkmcnt(3)
	v_mfma_f32_32x32x16_bf16 v[178:193], v[238:241], v[10:13], v[178:193]
	ds_read_b128 v[10:13], v236 offset:224
	ds_read_b128 v[14:17], v230 offset:8192
	ds_read_b128 v[238:241], v230 offset:12288
	s_waitcnt lgkmcnt(4)
	v_mfma_f32_32x32x16_bf16 v[194:209], v[250:253], v[246:249], v[194:209]
	s_waitcnt lgkmcnt(3)
	v_mfma_f32_32x32x16_bf16 v[178:193], v[6:9], v[246:249], v[178:193]
	s_waitcnt lgkmcnt(1)
	v_mfma_f32_32x32x16_bf16 v[194:209], v[14:17], v[10:13], v[194:209]
	s_waitcnt lgkmcnt(0)
	v_mfma_f32_32x32x16_bf16 v[178:193], v[238:241], v[10:13], v[178:193]
	v_exp_f32_e32 v166, v166
	v_exp_f32_e32 v167, v167
	v_exp_f32_e32 v168, v168
	v_exp_f32_e32 v169, v169
	s_nop 6
	v_exp_f32_e32 v2, v194
	v_exp_f32_e32 v194, v195
	v_exp_f32_e32 v195, v196
	v_exp_f32_e32 v196, v197
	v_exp_f32_e32 v197, v198
	v_exp_f32_e32 v198, v199
	v_exp_f32_e32 v199, v200
	v_exp_f32_e32 v200, v201
	v_exp_f32_e32 v201, v162
	v_exp_f32_e32 v237, v163
	v_exp_f32_e32 v238, v164
	v_exp_f32_e32 v239, v165
	v_cvt_pk_bf16_f32 v6, v201, v237
	v_cvt_pk_bf16_f32 v7, v238, v239
	v_cvt_pk_bf16_f32 v8, v166, v167
	v_cvt_pk_bf16_f32 v9, v168, v169
	ds_read_b64_tr_b16 v[10:11], v231 offset:49152
	ds_read_b64_tr_b16 v[12:13], v231 offset:51200
	v_cvt_pk_bf16_f32 v14, v2, v194
	ds_read_b64_tr_b16 v[162:163], v232 offset:49152
	ds_read_b64_tr_b16 v[164:165], v232 offset:51200
	v_cvt_pk_bf16_f32 v15, v195, v196
	v_cvt_pk_bf16_f32 v16, v197, v198
	v_cvt_pk_bf16_f32 v17, v199, v200
	s_waitcnt lgkmcnt(2)
	v_mfma_f32_32x32x16_bf16 v[82:97], v[6:9], v[10:13], v[82:97]
	v_exp_f32_e32 v202, v202
	v_exp_f32_e32 v203, v203
	v_exp_f32_e32 v204, v204
	v_exp_f32_e32 v205, v205
	v_exp_f32_e32 v206, v206
	v_exp_f32_e32 v207, v207
	v_exp_f32_e32 v208, v208
	v_mfma_f32_32x32x16_bf16 v[130:145], v[14:17], v[10:13], v[130:145]
	ds_read_b64_tr_b16 v[10:11], v233 offset:49152
	ds_read_b64_tr_b16 v[12:13], v233 offset:51200
	v_exp_f32_e32 v170, v170
	v_exp_f32_e32 v171, v171
	v_exp_f32_e32 v172, v172
	v_exp_f32_e32 v173, v173
	v_exp_f32_e32 v174, v174
	v_exp_f32_e32 v175, v175
	s_waitcnt lgkmcnt(2)
	v_mfma_f32_32x32x16_bf16 v[66:81], v[6:9], v[162:165], v[66:81]
	v_exp_f32_e32 v176, v176
	v_exp_f32_e32 v177, v177
	v_exp_f32_e32 v209, v209
	v_exp_f32_e32 v178, v178
	v_exp_f32_e32 v179, v179
	v_exp_f32_e32 v180, v180
	v_exp_f32_e32 v181, v181
	v_mfma_f32_32x32x16_bf16 v[114:129], v[14:17], v[162:165], v[114:129]
	ds_read_b64_tr_b16 v[162:163], v234 offset:49152
	ds_read_b64_tr_b16 v[164:165], v234 offset:51200
	v_add_f32_e32 v2, v178, v2
	v_add_f32_e32 v2, 0, v2
	v_add_f32_e32 v194, v179, v194
	v_add_f32_e32 v2, v194, v2
	v_add_f32_e32 v194, v180, v195
	s_waitcnt lgkmcnt(2)
	v_mfma_f32_32x32x16_bf16 v[34:49], v[6:9], v[10:13], v[34:49]
	v_add_f32_e32 v2, v194, v2
	v_add_f32_e32 v194, v181, v196
	v_add_f32_e32 v2, v194, v2
	v_exp_f32_e32 v182, v182
	v_exp_f32_e32 v183, v183
	v_exp_f32_e32 v184, v184
	v_exp_f32_e32 v194, v146
	v_mfma_f32_32x32x16_bf16 v[98:113], v[14:17], v[10:13], v[98:113]
	ds_read_b64_tr_b16 v[10:11], v231 offset:53248
	ds_read_b64_tr_b16 v[12:13], v231 offset:55296
	v_exp_f32_e32 v195, v147
	v_exp_f32_e32 v196, v148
	v_exp_f32_e32 v244, v149
	v_exp_f32_e32 v150, v150
	v_exp_f32_e32 v151, v151
	v_exp_f32_e32 v152, v152
	s_waitcnt lgkmcnt(2)
	v_mfma_f32_32x32x16_bf16 v[18:33], v[6:9], v[162:165], v[18:33]
	v_cvt_pk_bf16_f32 v6, v170, v171
	v_cvt_pk_bf16_f32 v7, v172, v173
	v_cvt_pk_bf16_f32 v8, v174, v175
	v_cvt_pk_bf16_f32 v9, v176, v177
	v_exp_f32_e32 v153, v153
	v_exp_f32_e32 v154, v154
	v_exp_f32_e32 v155, v155
	v_mfma_f32_32x32x16_bf16 v[50:65], v[14:17], v[162:165], v[50:65]
	v_cvt_pk_bf16_f32 v14, v202, v203
	ds_read_b64_tr_b16 v[162:163], v232 offset:53248
	ds_read_b64_tr_b16 v[164:165], v232 offset:55296
	v_cvt_pk_bf16_f32 v15, v204, v205
	v_cvt_pk_bf16_f32 v16, v206, v207
	v_cvt_pk_bf16_f32 v17, v208, v209
	v_exp_f32_e32 v156, v156
	s_waitcnt lgkmcnt(2)
	v_mfma_f32_32x32x16_bf16 v[82:97], v[6:9], v[10:13], v[82:97]
	v_exp_f32_e32 v157, v157
	v_exp_f32_e32 v158, v158
	v_exp_f32_e32 v159, v159
	v_exp_f32_e32 v160, v160
	v_exp_f32_e32 v161, v161
	s_sub_i32 s90, s88, s87
	v_add_u32_e32 v226, s90, v226
	v_add_u32_e32 v227, s90, v227
	v_add_u32_e32 v228, s90, v228
	v_add_u32_e32 v230, s90, v230
	s_mov_b32 s90, s87
	s_mov_b32 s87, s88
	s_mov_b32 s88, s89
	s_mov_b32 s89, s90
	s_add_u32 s42, s42, 0xa8000
	s_addc_u32 s43, s43, 0
	v_mfma_f32_32x32x16_bf16 v[130:145], v[14:17], v[10:13], v[130:145]
	ds_read_b64_tr_b16 v[10:11], v233 offset:53248
	ds_read_b64_tr_b16 v[12:13], v233 offset:55296
	s_cmp_eq_u32 s42, 0x5400000
	s_waitcnt lgkmcnt(2)
	v_mfma_f32_32x32x16_bf16 v[66:81], v[6:9], v[162:165], v[66:81]
	v_mfma_f32_32x32x16_bf16 v[114:129], v[14:17], v[162:165], v[114:129]
	ds_read_b64_tr_b16 v[162:163], v234 offset:53248
	ds_read_b64_tr_b16 v[164:165], v234 offset:55296
	s_waitcnt lgkmcnt(0)
	v_mfma_f32_32x32x16_bf16 v[18:33], v[6:9], v[162:165], v[18:33]
	v_mfma_f32_32x32x16_bf16 v[50:65], v[14:17], v[162:165], v[50:65]
	v_exp_f32_e32 v162, v185
	v_add_f32_e32 v163, v182, v197
	v_add_f32_e32 v2, v163, v2
	v_add_f32_e32 v163, v183, v198
	v_add_f32_e32 v2, v163, v2
	v_exp_f32_e32 v163, v186
	v_exp_f32_e32 v164, v188
	v_mfma_f32_32x32x16_bf16 v[34:49], v[6:9], v[10:13], v[34:49]
	v_cvt_pk_bf16_f32 v6, v194, v195
	v_cvt_pk_bf16_f32 v7, v196, v244
	v_cvt_pk_bf16_f32 v8, v150, v151
	v_cvt_pk_bf16_f32 v9, v152, v153
	v_exp_f32_e32 v165, v189
	v_mfma_f32_32x32x16_bf16 v[98:113], v[14:17], v[10:13], v[98:113]
	ds_read_b64_tr_b16 v[10:11], v231 offset:57344
	ds_read_b64_tr_b16 v[12:13], v231 offset:59392
	v_cvt_pk_bf16_f32 v14, v178, v179
	v_cvt_pk_bf16_f32 v15, v180, v181
	v_cvt_pk_bf16_f32 v16, v182, v183
	v_cvt_pk_bf16_f32 v17, v184, v162
	ds_read_b64_tr_b16 v[146:147], v232 offset:57344
	ds_read_b64_tr_b16 v[148:149], v232 offset:59392
	v_add_f32_e32 v178, v165, v205
	s_waitcnt lgkmcnt(2)
	v_mfma_f32_32x32x16_bf16 v[82:97], v[6:9], v[10:13], v[82:97]
	v_exp_f32_e32 v179, v190
	s_nop 0
	v_add_f32_e32 v180, v179, v206
	v_mfma_f32_32x32x16_bf16 v[130:145], v[14:17], v[10:13], v[130:145]
	v_add_f32_e32 v10, v184, v199
	ds_read_b128 v[182:185], v226 offset:4096
	v_add_f32_e32 v2, v10, v2
	v_add_f32_e32 v10, v162, v200
	v_exp_f32_e32 v162, v187
	ds_read_b128 v[186:189], v227
	v_add_f32_e32 v2, v10, v2
	v_add_f32_e32 v10, v163, v202
	v_add_f32_e32 v2, v10, v2
	v_add_f32_e32 v10, v162, v203
	v_add_f32_e32 v2, v10, v2
	v_add_f32_e32 v10, v164, v204
	ds_read_b128 v[202:205], v230
	v_add_f32_e32 v2, v10, v2
	v_add_f32_e32 v2, v178, v2
	v_exp_f32_e32 v178, v191
	ds_read_b64_tr_b16 v[10:11], v233 offset:57344
	ds_read_b64_tr_b16 v[12:13], v233 offset:59392
	s_waitcnt lgkmcnt(5)
	v_mfma_f32_32x32x16_bf16 v[66:81], v[6:9], v[146:149], v[66:81]
	v_add_f32_e32 v2, v180, v2
	v_exp_f32_e32 v180, v192
	v_add_f32_e32 v181, v178, v207
	v_add_f32_e32 v2, v181, v2
	v_exp_f32_e32 v181, v193
	ds_read_b128 v[190:193], v227 offset:4096
	v_mfma_f32_32x32x16_bf16 v[114:129], v[14:17], v[146:149], v[114:129]
	ds_read_b64_tr_b16 v[146:147], v234 offset:57344
	ds_read_b64_tr_b16 v[148:149], v234 offset:59392
	s_waitcnt lgkmcnt(3)
	v_mfma_f32_32x32x16_bf16 v[34:49], v[6:9], v[10:13], v[34:49]
	v_mfma_f32_32x32x16_bf16 v[98:113], v[14:17], v[10:13], v[98:113]
	v_add_f32_e32 v10, v180, v208
	v_add_f32_e32 v2, v10, v2
	ds_read_b64_tr_b16 v[10:11], v231 offset:61440
	ds_read_b64_tr_b16 v[12:13], v231 offset:63488
	s_waitcnt lgkmcnt(2)
	v_mfma_f32_32x32x16_bf16 v[18:33], v[6:9], v[146:149], v[18:33]
	v_cvt_pk_bf16_f32 v6, v154, v155
	v_cvt_pk_bf16_f32 v7, v156, v157
	v_cvt_pk_bf16_f32 v8, v158, v159
	v_cvt_pk_bf16_f32 v9, v160, v161
	v_mfma_f32_32x32x16_bf16 v[50:65], v[14:17], v[146:149], v[50:65]
	v_cvt_pk_bf16_f32 v14, v163, v162
	v_cvt_pk_bf16_f32 v15, v164, v165
	v_cvt_pk_bf16_f32 v16, v179, v178
	v_cvt_pk_bf16_f32 v17, v180, v181
	v_add_f32_e32 v162, v181, v209
	ds_read_b128 v[178:181], v226
	ds_read_b128 v[206:209], v230 offset:4096
	v_add_f32_e32 v2, v162, v2
	v_add_f32_e32 v4, v4, v2
	v_add_f32_e32 v2, v194, v201
	ds_read_b128 v[198:201], v228 offset:4096
	s_waitcnt lgkmcnt(3)
	v_mfma_f32_32x32x16_bf16 v[82:97], v[6:9], v[10:13], v[82:97]
	v_add_f32_e32 v2, 0, v2
	ds_read_b64_tr_b16 v[146:147], v232 offset:61440
	ds_read_b64_tr_b16 v[148:149], v232 offset:63488
	v_mfma_f32_32x32x16_bf16 v[130:145], v[14:17], v[10:13], v[130:145]
	v_add_f32_e32 v10, v195, v237
	v_add_f32_e32 v2, v10, v2
	v_add_f32_e32 v10, v196, v238
	ds_read_b128 v[194:197], v228
	v_add_f32_e32 v2, v10, v2
	v_add_f32_e32 v10, v244, v239
	v_add_f32_e32 v2, v10, v2
	v_add_f32_e32 v10, v150, v166
	v_add_f32_e32 v2, v10, v2
	v_add_f32_e32 v10, v151, v167
	v_add_f32_e32 v2, v10, v2
	v_add_f32_e32 v10, v152, v168
	s_waitcnt lgkmcnt(1)
	v_mfma_f32_32x32x16_bf16 v[66:81], v[6:9], v[146:149], v[66:81]
	v_add_f32_e32 v2, v10, v2
	ds_read_b64_tr_b16 v[10:11], v233 offset:61440
	ds_read_b64_tr_b16 v[12:13], v233 offset:63488
	v_add_f32_e32 v150, v153, v169
	v_add_f32_e32 v2, v150, v2
	v_add_f32_e32 v150, v154, v170
	v_add_f32_e32 v2, v150, v2
	v_add_f32_e32 v150, v155, v171
	v_mfma_f32_32x32x16_bf16 v[114:129], v[14:17], v[146:149], v[114:129]
	ds_read_b64_tr_b16 v[146:147], v234 offset:61440
	ds_read_b64_tr_b16 v[148:149], v234 offset:63488
	v_add_f32_e32 v2, v150, v2
	v_add_f32_e32 v150, v156, v172
	v_add_f32_e32 v2, v150, v2
	v_add_f32_e32 v150, v157, v173
	v_add_f32_e32 v2, v150, v2
	s_waitcnt lgkmcnt(2)
	v_mfma_f32_32x32x16_bf16 v[34:49], v[6:9], v[10:13], v[34:49]
	v_mfma_f32_32x32x16_bf16 v[98:113], v[14:17], v[10:13], v[98:113]
	v_add_f32_e32 v10, v158, v174
	v_add_f32_e32 v2, v10, v2
	v_add_f32_e32 v10, v159, v175
	v_add_f32_e32 v2, v10, v2
	v_add_f32_e32 v10, v160, v176
	v_add_f32_e32 v2, v10, v2
	v_add_f32_e32 v10, v161, v177
	s_waitcnt lgkmcnt(0)
	v_mfma_f32_32x32x16_bf16 v[18:33], v[6:9], v[146:149], v[18:33]
	v_add_f32_e32 v2, v10, v2
	v_add_f32_e32 v235, v235, v2
	v_mfma_f32_32x32x16_bf16 v[50:65], v[14:17], v[146:149], v[50:65]
	s_cbranch_scc0 .Lfast_loop

	.amdhsa_kernel _Z14fwd_megakernel4Args
		.amdhsa_group_segment_fixed_size 16384
		.amdhsa_private_segment_fixed_size 0
		.amdhsa_kernarg_size 448
		.amdhsa_user_sgpr_count 2
		.amdhsa_user_sgpr_dispatch_ptr 0
		.amdhsa_user_sgpr_queue_ptr 0
		.amdhsa_user_sgpr_kernarg_segment_ptr 1
		.amdhsa_user_sgpr_dispatch_id 0
		.amdhsa_user_sgpr_kernarg_preload_length 0
		.amdhsa_user_sgpr_kernarg_preload_offset 0
		.amdhsa_user_sgpr_private_segment_size 0
		.amdhsa_uses_dynamic_stack 0
		.amdhsa_enable_private_segment 0
		.amdhsa_system_sgpr_workgroup_id_x 1
		.amdhsa_system_sgpr_workgroup_id_y 0
		.amdhsa_system_sgpr_workgroup_id_z 0
		.amdhsa_system_sgpr_workgroup_info 0
		.amdhsa_system_vgpr_workitem_id 2
		.amdhsa_next_free_vgpr 256
		.amdhsa_next_free_sgpr 98
		.amdhsa_accum_offset 256
		.amdhsa_reserve_vcc 1
		.amdhsa_float_round_mode_32 0
		.amdhsa_float_round_mode_16_64 0
		.amdhsa_float_denorm_mode_32 3
		.amdhsa_float_denorm_mode_16_64 3
		.amdhsa_dx10_clamp 1
		.amdhsa_ieee_mode 1
		.amdhsa_fp16_overflow 0
		.amdhsa_tg_split 0
		.amdhsa_exception_fp_ieee_invalid_op 0
		.amdhsa_exception_fp_denorm_src 0
		.amdhsa_exception_fp_ieee_div_zero 0
		.amdhsa_exception_fp_ieee_overflow 0
		.amdhsa_exception_fp_ieee_underflow 0
		.amdhsa_exception_fp_ieee_inexact 0
		.amdhsa_exception_int_div_zero 0
	.end_amdhsa_kernel

amdhsa.kernels:
  - .agpr_count:     0
    .args:
      - .offset:         0
        .size:           192
        .value_kind:     by_value
      - .offset:         192
        .size:           4
        .value_kind:     hidden_block_count_x
      - .offset:         196
        .size:           4
        .value_kind:     hidden_block_count_y
      - .offset:         200
        .size:           4
        .value_kind:     hidden_block_count_z
      - .offset:         204
        .size:           2
        .value_kind:     hidden_group_size_x
      - .offset:         206
        .size:           2
        .value_kind:     hidden_group_size_y
      - .offset:         208
        .size:           2
        .value_kind:     hidden_group_size_z
      - .offset:         210
        .size:           2
        .value_kind:     hidden_remainder_x
      - .offset:         212
        .size:           2
        .value_kind:     hidden_remainder_y
      - .offset:         214
        .size:           2
        .value_kind:     hidden_remainder_z
      - .offset:         232
        .size:           8
        .value_kind:     hidden_global_offset_x
      - .offset:         240
        .size:           8
        .value_kind:     hidden_global_offset_y
      - .offset:         248
        .size:           8
        .value_kind:     hidden_global_offset_z
      - .offset:         256
        .size:           2
        .value_kind:     hidden_grid_dims
      - .offset:         280
        .size:           8
        .value_kind:     hidden_multigrid_sync_arg
      - .offset:         312
        .size:           4
        .value_kind:     hidden_dynamic_lds_size
    .group_segment_fixed_size: 16384
    .kernarg_segment_align: 8
    .kernarg_segment_size: 448
    .language:       OpenCL C
    .language_version:
      - 2
      - 0
    .max_flat_workgroup_size: 512
    .name:           _Z14fwd_megakernel4Args
    .private_segment_fixed_size: 0
    .sgpr_count:     104
    .sgpr_spill_count: 2
    .symbol:         _Z14fwd_megakernel4Args.kd
    .uniform_work_group_size: 1
    .uses_dynamic_stack: false
    .vgpr_count:     256
    .vgpr_spill_count: 0
    .wavefront_size: 64
